# GEMM phase prologues: 4 redundant vmcnt(0) drains removed (operands already covered by earlier vmcnt(2))
# baseline (speedup 1.0000x reference)
; __device__ __forceinline__ int opaque_tid() { int t = threadIdx.x; asm volatile("" : "+v"(t)); return t; }
; #define PG8_LAS __attribute__((address_space(3)))
; #define PG8_STAGE(bufoff, gbase, voff) do { _Pragma("unroll") for (int _i = 0; _i < 2; ++_i) \
;         __builtin_amdgcn_global_load_lds((const unsigned*)((const char*)(gbase) + (voff)[_i]), (PG8_LAS unsigned*)(lds + (bufoff) + ldsw + _i * 8192), 16, 0, 0); } while (0)
; #define PG8_WAIT_V(n) asm volatile("s_waitcnt vmcnt(" #n ")" ::: "memory")
; #define PG8_BAR __builtin_amdgcn_s_barrier()
; __device__ __forceinline__ void rstd_store(PG8_LAS float* tab, const RstdIni& ini, int par) {
;     const int tid = opaque_tid();
;     float s = ((ini.a[0] + ini.a[1]) + (ini.a[2] + ini.a[3])) + ((ini.b[0] + ini.b[1]) + (ini.b[2] + ini.b[3]));
;     s += __shfl_xor(s, 1);
;     if (!(tid & 1)) tab[par * BM + (tid >> 1)] = __builtin_amdgcn_rsqf(s * (1.0f / 1024.0f) + 1e-6f);
; }
; template <class Epi>
; __device__ __forceinline__ void gemm_phase(PG8_LAS unsigned char* lds, const Gemm g, const StaticOrder& S, const Epi& E) {
;     ...
;     E.init_load(acc, ini, cur, wr, wc, fr, fq);
;     bf16x8 At[4][2], B0[2][2], B1[2][2];
;     const char* cA = (const char*)g.A + (size_t)cur.pm * tstepA + (size_t)cur.pn * g.a_pn * 2; const char* cB = (const char*)g.Bt + (size_t)cur.pn * tstepB;
;     PG8_STAGE(PG8_SB(0, 0), cB, voffB); PG8_STAGE(PG8_SB(0, 1), cB + hstepB, voffB); PG8_STAGE(PG8_SA(0, 0), cA, voffA); PG8_STAGE(PG8_SA(0, 1), cA + hstepA, voffA);
;     if (wr == 1) PG8_BAR;
;     PG8_WAIT_V(2); PG8_BAR;
;     PG8_STAGE(PG8_SB(1, 0), cB + kstepB, voffB); PG8_STAGE(PG8_SA(1, 0), cA + kstepA, voffA); PG8_STAGE(PG8_SB(1, 1), cB + hstepB + kstepB, voffB);
;     PG8_WAIT_V(6); PG8_BAR;
;     E.init_apply(acc, ini, cur, wr, wc, fr, fq, 0);
.LBB0_34:
	v_mov_b32_e32 v145, v99
	v_lshl_add_u64 v[18:19], s[30:31], 0, v[144:145]
	v_mov_b32_e32 v141, v99
	v_lshl_add_u64 v[20:21], s[30:31], 0, v[140:141]
	v_mov_b32_e32 v147, v99
	s_add_i32 m0, s9, 0x18000
	v_lshl_add_u64 v[18:19], v[18:19], 0, s[34:35]
	v_lshl_add_u64 v[22:23], s[22:23], 0, v[146:147]
	v_mov_b32_e32 v143, v99
	s_waitcnt vmcnt(2)
	s_barrier
	global_load_lds_dwordx4 v[18:19], off
	v_lshl_add_u64 v[18:19], v[20:21], 0, s[34:35]
	s_add_i32 m0, s9, 0x1a000
	s_add_i32 s27, s9, 0x8000
	s_add_i32 s42, s9, 0xa000
	v_lshl_add_u64 v[24:25], s[22:23], 0, v[142:143]
	global_load_lds_dwordx4 v[18:19], off
	v_lshl_add_u64 v[18:19], v[22:23], 0, s[34:35]
	s_mov_b32 m0, s27
	s_add_u32 s0, s30, 0x40080
	global_load_lds_dwordx4 v[18:19], off
	v_lshl_add_u64 v[18:19], v[24:25], 0, s[34:35]
	s_mov_b32 m0, s42
	s_addc_u32 s1, s31, 0
	global_load_lds_dwordx4 v[18:19], off
	s_add_i32 m0, s9, 0x1c000
	v_lshl_add_u64 v[18:19], s[0:1], 0, v[144:145]
	global_load_lds_dwordx4 v[18:19], off
	v_lshl_add_u64 v[18:19], s[0:1], 0, v[140:141]
	s_add_i32 m0, s9, 0x1e000
	v_add_f32_e32 v17, v6, v7
	global_load_lds_dwordx4 v[18:19], off
	v_add_f32_e32 v18, v8, v9
	v_add_f32_e32 v17, v17, v18
	v_add_f32_e32 v18, v2, v3
	v_add_f32_e32 v19, v4, v5
	v_add_f32_e32 v18, v18, v19
	v_add_f32_e32 v17, v17, v18
	v_xor_b32_e32 v18, 1, v212
	v_cmp_lt_i32_e32 vcc, v18, v213
	s_waitcnt vmcnt(6)
	s_barrier
	s_nop 0
	v_cndmask_b32_e32 v18, v212, v18, vcc
	v_lshlrev_b32_e32 v176, 2, v18
	ds_bpermute_b32 v19, v176, v17
	v_mov_b32_e32 v18, v0
	s_nop 0
	v_and_b32_e32 v20, 1, v18
	v_cmp_eq_u32_e32 vcc, 0, v20
	s_and_saveexec_b64 s[0:1], vcc
	s_cbranch_execz .LBB0_36
	s_waitcnt lgkmcnt(0)
	v_add_f32_e32 v17, v17, v19
	v_fmamk_f32 v17, v17, 0x3a800000, v1
	v_rsq_f32_e32 v17, v17
	v_lshl_add_u32 v18, v18, 1, 0
	v_add_u32_e32 v18, 0x21000, v18
	ds_write_b32 v18, v17

; __device__ __forceinline__ int opaque_tid() { int t = threadIdx.x; asm volatile("" : "+v"(t)); return t; }
; #define PG8_LAS __attribute__((address_space(3)))
; #define PG8_STAGE(bufoff, gbase, voff) do { _Pragma("unroll") for (int _i = 0; _i < 2; ++_i) \
;         __builtin_amdgcn_global_load_lds((const unsigned*)((const char*)(gbase) + (voff)[_i]), (PG8_LAS unsigned*)(lds + (bufoff) + ldsw + _i * 8192), 16, 0, 0); } while (0)
; #define PG8_WAIT_V(n) asm volatile("s_waitcnt vmcnt(" #n ")" ::: "memory")
; #define PG8_BAR __builtin_amdgcn_s_barrier()
; __device__ __forceinline__ void rstd_store(PG8_LAS float* tab, const RstdIni& ini, int par) {
;     const int tid = opaque_tid();
;     float s = ((ini.a[0] + ini.a[1]) + (ini.a[2] + ini.a[3])) + ((ini.b[0] + ini.b[1]) + (ini.b[2] + ini.b[3]));
;     s += __shfl_xor(s, 1);
;     if (!(tid & 1)) tab[par * BM + (tid >> 1)] = __builtin_amdgcn_rsqf(s * (1.0f / 1024.0f) + 1e-6f);
; }
; template <class Epi>
; __device__ __forceinline__ void gemm_phase(PG8_LAS unsigned char* lds, const Gemm g, const StaticOrder& S, const Epi& E) {
;     ...
;     E.init_load(acc, ini, cur, wr, wc, fr, fq);
;     bf16x8 At[4][2], B0[2][2], B1[2][2];
;     const char* cA = (const char*)g.A + (size_t)cur.pm * tstepA + (size_t)cur.pn * g.a_pn * 2; const char* cB = (const char*)g.Bt + (size_t)cur.pn * tstepB;
;     PG8_STAGE(PG8_SB(0, 0), cB, voffB); PG8_STAGE(PG8_SB(0, 1), cB + hstepB, voffB); PG8_STAGE(PG8_SA(0, 0), cA, voffA); PG8_STAGE(PG8_SA(0, 1), cA + hstepA, voffA);
;     if (wr == 1) PG8_BAR;
;     PG8_WAIT_V(2); PG8_BAR;
;     PG8_STAGE(PG8_SB(1, 0), cB + kstepB, voffB); PG8_STAGE(PG8_SA(1, 0), cA + kstepA, voffA); PG8_STAGE(PG8_SB(1, 1), cB + hstepB + kstepB, voffB);
;     PG8_WAIT_V(6); PG8_BAR;
;     E.init_apply(acc, ini, cur, wr, wc, fr, fq, 0);
.LBB0_253:
	v_readlane_b32 s0, v255, 18
	v_mov_b32_e32 v149, v99
	v_readlane_b32 s1, v255, 19
	v_mov_b32_e32 v145, v99
	v_mov_b32_e32 v151, v99
	v_lshl_add_u64 v[18:19], s[0:1], 0, v[148:149]
	v_lshl_add_u64 v[20:21], s[0:1], 0, v[144:145]
	v_readlane_b32 s0, v255, 14
	v_readlane_b32 s1, v255, 15
	s_add_i32 m0, s3, 0x18000
	v_lshl_add_u64 v[18:19], v[18:19], 0, s[34:35]
	v_lshl_add_u64 v[22:23], s[0:1], 0, v[150:151]
	v_mov_b32_e32 v147, v99
	s_waitcnt vmcnt(2)
	s_barrier
	global_load_lds_dwordx4 v[18:19], off
	v_lshl_add_u64 v[18:19], v[20:21], 0, s[34:35]
	s_add_i32 m0, s3, 0x1a000
	s_add_i32 s25, s3, 0x8000
	v_lshl_add_u64 v[24:25], s[0:1], 0, v[146:147]
	global_load_lds_dwordx4 v[18:19], off
	v_lshl_add_u64 v[18:19], v[22:23], 0, s[34:35]
	s_mov_b32 m0, s25
	s_add_i32 s26, s3, 0xa000
	v_readlane_b32 s0, v255, 20
	global_load_lds_dwordx4 v[18:19], off
	v_lshl_add_u64 v[18:19], v[24:25], 0, s[34:35]
	s_mov_b32 m0, s26
	v_readlane_b32 s1, v255, 21
	global_load_lds_dwordx4 v[18:19], off
	s_add_i32 m0, s3, 0x1c000
	v_lshl_add_u64 v[18:19], s[0:1], 0, v[148:149]
	global_load_lds_dwordx4 v[18:19], off
	v_lshl_add_u64 v[18:19], s[0:1], 0, v[144:145]
	s_add_i32 m0, s3, 0x1e000
	v_add_f32_e32 v17, v6, v7
	global_load_lds_dwordx4 v[18:19], off
	v_add_f32_e32 v18, v8, v9
	v_add_f32_e32 v17, v17, v18
	v_add_f32_e32 v18, v2, v3
	v_add_f32_e32 v19, v4, v5
	v_add_f32_e32 v18, v18, v19
	v_add_f32_e32 v17, v17, v18
	v_xor_b32_e32 v18, 1, v212
	v_cmp_lt_i32_e32 vcc, v18, v213
	s_waitcnt vmcnt(6)
	s_barrier
	s_nop 0
	v_cndmask_b32_e32 v18, v212, v18, vcc
	v_lshlrev_b32_e32 v168, 2, v18
	ds_bpermute_b32 v19, v168, v17
	v_mov_b32_e32 v18, v0
	s_nop 0
	v_and_b32_e32 v20, 1, v18
	v_cmp_eq_u32_e32 vcc, 0, v20
	s_and_saveexec_b64 s[0:1], vcc
	s_cbranch_execz .LBB0_255
	s_waitcnt lgkmcnt(0)
	v_add_f32_e32 v17, v17, v19
	v_fmamk_f32 v17, v17, 0x3a800000, v1
	v_rsq_f32_e32 v17, v17
	v_lshl_add_u32 v18, v18, 1, 0
	v_add_u32_e32 v18, 0x21000, v18
	ds_write_b32 v18, v17

; __device__ __forceinline__ int opaque_tid() { int t = threadIdx.x; asm volatile("" : "+v"(t)); return t; }
; #define PG8_LAS __attribute__((address_space(3)))
; #define PG8_STAGE(bufoff, gbase, voff) do { _Pragma("unroll") for (int _i = 0; _i < 2; ++_i) \
;         __builtin_amdgcn_global_load_lds((const unsigned*)((const char*)(gbase) + (voff)[_i]), (PG8_LAS unsigned*)(lds + (bufoff) + ldsw + _i * 8192), 16, 0, 0); } while (0)
; #define PG8_WAIT_V(n) asm volatile("s_waitcnt vmcnt(" #n ")" ::: "memory")
; #define PG8_BAR __builtin_amdgcn_s_barrier()
; __device__ __forceinline__ void rstd_store(PG8_LAS float* tab, const RstdIni& ini, int par) {
;     const int tid = opaque_tid();
;     float s = ((ini.a[0] + ini.a[1]) + (ini.a[2] + ini.a[3])) + ((ini.b[0] + ini.b[1]) + (ini.b[2] + ini.b[3]));
;     s += __shfl_xor(s, 1);
;     if (!(tid & 1)) tab[par * BM + (tid >> 1)] = __builtin_amdgcn_rsqf(s * (1.0f / 1024.0f) + 1e-6f);
; }
; template <class Epi>
; __device__ __forceinline__ void gemm_phase(PG8_LAS unsigned char* lds, const Gemm g, const StaticOrder& S, const Epi& E) {
;     ...
;     E.init_load(acc, ini, cur, wr, wc, fr, fq);
;     bf16x8 At[4][2], B0[2][2], B1[2][2];
;     const char* cA = (const char*)g.A + (size_t)cur.pm * tstepA + (size_t)cur.pn * g.a_pn * 2; const char* cB = (const char*)g.Bt + (size_t)cur.pn * tstepB;
;     PG8_STAGE(PG8_SB(0, 0), cB, voffB); PG8_STAGE(PG8_SB(0, 1), cB + hstepB, voffB); PG8_STAGE(PG8_SA(0, 0), cA, voffA); PG8_STAGE(PG8_SA(0, 1), cA + hstepA, voffA);
;     if (wr == 1) PG8_BAR;
;     PG8_WAIT_V(2); PG8_BAR;
;     PG8_STAGE(PG8_SB(1, 0), cB + kstepB, voffB); PG8_STAGE(PG8_SA(1, 0), cA + kstepA, voffA); PG8_STAGE(PG8_SB(1, 1), cB + hstepB + kstepB, voffB);
;     PG8_WAIT_V(6); PG8_BAR;
;     E.init_apply(acc, ini, cur, wr, wc, fr, fq, 0);
.LBB0_368:
	v_mov_b32_e32 v181, v99
	v_lshl_add_u64 v[18:19], s[30:31], 0, v[180:181]
	v_mov_b32_e32 v177, v99
	v_readlane_b32 s0, v255, 14
	v_lshl_add_u64 v[20:21], s[30:31], 0, v[176:177]
	v_mov_b32_e32 v183, v99
	v_readlane_b32 s1, v255, 15
	s_add_i32 m0, s27, 0x18000
	v_lshl_add_u64 v[18:19], v[18:19], 0, s[34:35]
	v_lshl_add_u64 v[22:23], s[0:1], 0, v[182:183]
	v_mov_b32_e32 v179, v99
	s_waitcnt vmcnt(2)
	s_barrier
	global_load_lds_dwordx4 v[18:19], off
	v_lshl_add_u64 v[18:19], v[20:21], 0, s[34:35]
	s_add_i32 m0, s27, 0x1a000
	s_add_i32 s81, s27, 0x8000
	s_add_i32 s86, s27, 0xa000
	v_lshl_add_u64 v[24:25], s[0:1], 0, v[178:179]
	global_load_lds_dwordx4 v[18:19], off
	v_lshl_add_u64 v[18:19], v[22:23], 0, s[34:35]
	s_mov_b32 m0, s81
	s_add_u32 s0, s30, 0x40080
	global_load_lds_dwordx4 v[18:19], off
	v_lshl_add_u64 v[18:19], v[24:25], 0, s[34:35]
	s_mov_b32 m0, s86
	s_addc_u32 s1, s31, 0
	global_load_lds_dwordx4 v[18:19], off
	s_add_i32 m0, s27, 0x1c000
	v_lshl_add_u64 v[18:19], s[0:1], 0, v[180:181]
	global_load_lds_dwordx4 v[18:19], off
	v_lshl_add_u64 v[18:19], s[0:1], 0, v[176:177]
	s_add_i32 m0, s27, 0x1e000
	v_add_f32_e32 v17, v6, v7
	global_load_lds_dwordx4 v[18:19], off
	v_add_f32_e32 v18, v8, v9
	v_add_f32_e32 v17, v17, v18
	v_add_f32_e32 v18, v2, v3
	v_add_f32_e32 v19, v4, v5
	v_add_f32_e32 v18, v18, v19
	v_add_f32_e32 v17, v17, v18
	v_xor_b32_e32 v18, 1, v212
	v_cmp_lt_i32_e32 vcc, v18, v213
	s_waitcnt vmcnt(6)
	s_barrier
	s_mov_b64 s[68:69], s[92:93]
	v_cndmask_b32_e32 v18, v212, v18, vcc
	v_lshlrev_b32_e32 v208, 2, v18
	ds_bpermute_b32 v19, v208, v17
	v_mov_b32_e32 v18, v0
	s_nop 0
	v_and_b32_e32 v20, 1, v18
	v_cmp_eq_u32_e32 vcc, 0, v20
	s_and_saveexec_b64 s[0:1], vcc
	v_readlane_b32 s10, v253, 37
	v_readlane_b32 s11, v253, 38
	s_movk_i32 s47, 0x61
	s_cbranch_execz .LBB0_370
	s_waitcnt lgkmcnt(0)
	v_add_f32_e32 v17, v17, v19
	v_fmamk_f32 v17, v17, 0x3a800000, v1
	v_rsq_f32_e32 v17, v17
	v_lshl_add_u32 v18, v18, 1, 0
	v_add_u32_e32 v18, 0x21000, v18
	ds_write_b32 v18, v17

;     __device__ __forceinline__ void init_apply(f32x4 (&acc)[2][2][4][2], const Ini& ini, const Unit& u, int wr, int wc, int fr, int fq, int) const {
;         const int col0 = u.pn * BM + wc * 64 + 8 * fq;
;         f32x4 is[2][2];
; #pragma unroll
;         for (int bj = 0; bj < 2; ++bj)
; #pragma unroll
;             for (int n = 0; n < 2; ++n) { is[bj][n] = (f32x4){1.f, 1.f, 1.f, 1.f};
;                 if (cscale) { const f32x4 sc = *(const f32x4*)(cscale + col0 + bj * 32 + 4 * n);
; #pragma unroll
;                     for (int j = 0; j < 4; ++j) is[bj][n][j] = __builtin_amdgcn_rcpf(sc[j]); } }
; #pragma unroll
;         for (int ai = 0; ai < 2; ++ai)
; #pragma unroll
;             for (int m = 0; m < 4; ++m)
; #pragma unroll
;                 for (int bj = 0; bj < 2; ++bj) { const u32x4 w = ini.x[ai][m][bj];
;                     acc[ai][bj][m][0] = (f32x4){__uint_as_float(w.x << 16), __uint_as_float(w.x & 0xffff0000u), __uint_as_float(w.y << 16), __uint_as_float(w.y & 0xffff0000u)} * is[bj][0];
;                     acc[ai][bj][m][1] = (f32x4){__uint_as_float(w.z << 16), __uint_as_float(w.z & 0xffff0000u), __uint_as_float(w.w << 16), __uint_as_float(w.w & 0xffff0000u)} * is[bj][1]; }
.LBB0_471:
	v_or_b32_e32 v158, s13, v36
	v_lshlrev_b32_e32 v34, 6, v158
	v_lshlrev_b32_e32 v35, 4, v154
	s_movk_i32 s6, 0x3c0
	v_lshlrev_b32_e32 v37, 2, v158
	v_and_or_b32 v34, v34, s6, v35
	s_lshl_b32 s6, s10, 13
	v_and_b32_e32 v37, 32, v37
	v_bitop3_b32 v156, v34, s6, v37 bitop3:0xde
	v_lshl_or_b32 v34, v36, 6, v35
	v_lshlrev_b32_e32 v35, 2, v36
	s_lshl_b32 s6, s27, 12
	v_and_b32_e32 v35, 32, v35
	v_bitop3_b32 v159, v34, s6, v35 bitop3:0xde
	v_lshlrev_b32_e32 v34, 16, v62
	v_and_b32_e32 v35, 0xffff0000, v62
	v_lshlrev_b32_e32 v36, 16, v63
	v_and_b32_e32 v37, 0xffff0000, v63
	v_lshlrev_b32_e32 v62, 16, v64
	v_and_b32_e32 v63, 0xffff0000, v64
	v_pk_mul_f32 v[100:101], v[132:133], v[62:63]
	v_lshlrev_b32_e32 v62, 16, v30
	v_and_b32_e32 v63, 0xffff0000, v30
	v_lshlrev_b32_e32 v30, 16, v31
	v_and_b32_e32 v31, 0xffff0000, v31
	v_pk_mul_f32 v[106:107], v[144:145], v[30:31]
	v_lshlrev_b32_e32 v30, 16, v32
	v_and_b32_e32 v31, 0xffff0000, v32
	v_lshlrev_b32_e32 v32, 16, v33
	v_and_b32_e32 v33, 0xffff0000, v33
	v_pk_mul_f32 v[130:131], v[146:147], v[32:33]
	v_pk_mul_f32 v[128:129], v[134:135], v[30:31]
	v_lshlrev_b32_e32 v30, 16, v58
	v_and_b32_e32 v31, 0xffff0000, v58
	v_lshlrev_b32_e32 v32, 16, v59
	v_and_b32_e32 v33, 0xffff0000, v59
	v_lshlrev_b32_e32 v58, 16, v60
	v_and_b32_e32 v59, 0xffff0000, v60
	v_pk_mul_f32 v[90:91], v[132:133], v[58:59]
	v_lshlrev_b32_e32 v58, 16, v22
	v_and_b32_e32 v59, 0xffff0000, v22
	v_lshlrev_b32_e32 v22, 16, v23
	v_and_b32_e32 v23, 0xffff0000, v23
	v_pk_mul_f32 v[84:85], v[144:145], v[22:23]
	v_lshlrev_b32_e32 v22, 16, v24
	v_and_b32_e32 v23, 0xffff0000, v24
	v_lshlrev_b32_e32 v24, 16, v25
	v_and_b32_e32 v25, 0xffff0000, v25
	v_pk_mul_f32 v[126:127], v[146:147], v[24:25]
	v_pk_mul_f32 v[124:125], v[134:135], v[22:23]
	v_lshlrev_b32_e32 v22, 16, v54
	v_and_b32_e32 v23, 0xffff0000, v54
	v_lshlrev_b32_e32 v24, 16, v55
	v_and_b32_e32 v25, 0xffff0000, v55
	v_lshlrev_b32_e32 v54, 16, v56
	v_and_b32_e32 v55, 0xffff0000, v56
	v_pk_mul_f32 v[78:79], v[132:133], v[54:55]
	v_lshlrev_b32_e32 v54, 16, v14
	v_and_b32_e32 v55, 0xffff0000, v14
	v_lshlrev_b32_e32 v14, 16, v15
	v_and_b32_e32 v15, 0xffff0000, v15
	v_pk_mul_f32 v[72:73], v[144:145], v[14:15]
	v_lshlrev_b32_e32 v14, 16, v16
	v_and_b32_e32 v15, 0xffff0000, v16
	v_lshlrev_b32_e32 v16, 16, v17
	v_and_b32_e32 v17, 0xffff0000, v17
	v_pk_mul_f32 v[122:123], v[146:147], v[16:17]
	v_pk_mul_f32 v[120:121], v[134:135], v[14:15]
	v_lshlrev_b32_e32 v14, 16, v50
	v_and_b32_e32 v15, 0xffff0000, v50
	v_lshlrev_b32_e32 v16, 16, v51
	v_and_b32_e32 v17, 0xffff0000, v51
	v_lshlrev_b32_e32 v50, 16, v52
	v_and_b32_e32 v51, 0xffff0000, v52
	v_pk_mul_f32 v[104:105], v[142:143], v[62:63]
	v_lshlrev_b32_e32 v56, 16, v57
	v_and_b32_e32 v57, 0xffff0000, v57
	v_pk_mul_f32 v[62:63], v[132:133], v[50:51]
	v_lshlrev_b32_e32 v50, 16, v18
	v_and_b32_e32 v51, 0xffff0000, v18
	v_lshlrev_b32_e32 v18, 16, v19
	v_and_b32_e32 v19, 0xffff0000, v19
	v_pk_mul_f32 v[80:81], v[140:141], v[56:57]
	v_pk_mul_f32 v[56:57], v[144:145], v[18:19]
	v_lshlrev_b32_e32 v18, 16, v20
	v_and_b32_e32 v19, 0xffff0000, v20
	v_lshlrev_b32_e32 v20, 16, v21
	v_and_b32_e32 v21, 0xffff0000, v21
	v_pk_mul_f32 v[114:115], v[146:147], v[20:21]
	v_pk_mul_f32 v[112:113], v[134:135], v[18:19]
	v_lshlrev_b32_e32 v18, 16, v46
	v_and_b32_e32 v19, 0xffff0000, v46
	v_lshlrev_b32_e32 v20, 16, v47
	v_and_b32_e32 v21, 0xffff0000, v47
	v_lshlrev_b32_e32 v46, 16, v48
	v_and_b32_e32 v47, 0xffff0000, v48
	v_pk_mul_f32 v[74:75], v[132:133], v[46:47]
	v_lshlrev_b32_e32 v46, 16, v10
	v_and_b32_e32 v47, 0xffff0000, v10
	v_lshlrev_b32_e32 v10, 16, v11
	v_and_b32_e32 v11, 0xffff0000, v11
	v_pk_mul_f32 v[68:69], v[144:145], v[10:11]
	v_lshlrev_b32_e32 v10, 16, v12
	v_and_b32_e32 v11, 0xffff0000, v12
	v_lshlrev_b32_e32 v12, 16, v13
	v_and_b32_e32 v13, 0xffff0000, v13
	v_pk_mul_f32 v[118:119], v[146:147], v[12:13]
	v_pk_mul_f32 v[116:117], v[134:135], v[10:11]
	v_lshlrev_b32_e32 v10, 16, v42
	v_and_b32_e32 v11, 0xffff0000, v42
	v_lshlrev_b32_e32 v12, 16, v43
	v_and_b32_e32 v13, 0xffff0000, v43
;     __device__ __forceinline__ void init_apply(f32x4 (&acc)[2][2][4][2], const Ini& ini, const Unit& u, int wr, int wc, int fr, int fq, int) const {
;     ...
;         for (int ai = 0; ai < 2; ++ai)
; #pragma unroll
;             for (int m = 0; m < 4; ++m)
; #pragma unroll
;                 for (int bj = 0; bj < 2; ++bj) { const u32x4 w = ini.x[ai][m][bj];
;                     acc[ai][bj][m][0] = (f32x4){__uint_as_float(w.x << 16), __uint_as_float(w.x & 0xffff0000u), __uint_as_float(w.y << 16), __uint_as_float(w.y & 0xffff0000u)} * is[bj][0];
;                     acc[ai][bj][m][1] = (f32x4){__uint_as_float(w.z << 16), __uint_as_float(w.z & 0xffff0000u), __uint_as_float(w.w << 16), __uint_as_float(w.w & 0xffff0000u)} * is[bj][1]; }
	v_lshlrev_b32_e32 v42, 16, v44
	v_and_b32_e32 v43, 0xffff0000, v44
	v_lshlrev_b32_e32 v64, 16, v65
	v_and_b32_e32 v65, 0xffff0000, v65
	v_pk_mul_f32 v[82:83], v[142:143], v[58:59]
	v_lshlrev_b32_e32 v52, 16, v53
	v_and_b32_e32 v53, 0xffff0000, v53
	v_pk_mul_f32 v[58:59], v[132:133], v[42:43]
	v_lshlrev_b32_e32 v42, 16, v6
	v_and_b32_e32 v43, 0xffff0000, v6
	v_lshlrev_b32_e32 v6, 16, v7
	v_and_b32_e32 v7, 0xffff0000, v7
	v_pk_mul_f32 v[102:103], v[140:141], v[64:65]
	v_pk_mul_f32 v[64:65], v[140:141], v[52:53]
	v_pk_mul_f32 v[52:53], v[144:145], v[6:7]
	v_lshlrev_b32_e32 v6, 16, v8
	v_and_b32_e32 v7, 0xffff0000, v8
	v_lshlrev_b32_e32 v8, 16, v9
	v_and_b32_e32 v9, 0xffff0000, v9
	s_and_b64 s[6:7], s[30:31], exec
	v_pk_mul_f32 v[110:111], v[146:147], v[8:9]
	v_pk_mul_f32 v[108:109], v[134:135], v[6:7]
	v_lshlrev_b32_e32 v6, 16, v38
	v_and_b32_e32 v7, 0xffff0000, v38
	v_lshlrev_b32_e32 v8, 16, v39
	v_and_b32_e32 v9, 0xffff0000, v39
	v_lshlrev_b32_e32 v38, 16, v40
	v_and_b32_e32 v39, 0xffff0000, v40
	s_cselect_b32 s46, 7, 15
	s_and_b64 s[6:7], s[22:23], exec
	v_lshlrev_b32_e32 v60, 16, v61
	v_and_b32_e32 v61, 0xffff0000, v61
	v_pk_mul_f32 v[66:67], v[142:143], v[46:47]
	v_lshlrev_b32_e32 v44, 16, v45
	v_and_b32_e32 v45, 0xffff0000, v45
	v_pk_mul_f32 v[46:47], v[132:133], v[38:39]
	v_lshlrev_b32_e32 v38, 16, v2
	v_and_b32_e32 v39, 0xffff0000, v2
	v_lshlrev_b32_e32 v2, 16, v3
	v_and_b32_e32 v3, 0xffff0000, v3
	s_cselect_b32 s88, 7, 15
	s_cmpk_lt_u32 s3, 0x100
	v_pk_mul_f32 v[92:93], v[140:141], v[60:61]
	v_pk_mul_f32 v[60:61], v[140:141], v[44:45]
	v_pk_mul_f32 v[44:45], v[144:145], v[2:3]
	v_lshlrev_b32_e32 v2, 16, v4
	v_and_b32_e32 v3, 0xffff0000, v4
	v_lshlrev_b32_e32 v4, 16, v5
	v_and_b32_e32 v5, 0xffff0000, v5
	s_cselect_b64 s[6:7], -1, 0
	v_lshlrev_b32_e32 v48, 16, v49
	v_and_b32_e32 v49, 0xffff0000, v49
	v_lshlrev_b32_e32 v40, 16, v41
	v_and_b32_e32 v41, 0xffff0000, v41
	v_pk_mul_f32 v[96:97], v[146:147], v[4:5]
	v_pk_mul_f32 v[94:95], v[134:135], v[2:3]
	v_lshlrev_b32_e32 v2, 16, v26
	v_and_b32_e32 v3, 0xffff0000, v26
	v_lshlrev_b32_e32 v4, 16, v27
	v_and_b32_e32 v5, 0xffff0000, v27
	v_lshlrev_b32_e32 v26, 16, v28
	v_and_b32_e32 v27, 0xffff0000, v28
	v_lshlrev_b32_e32 v28, 16, v29
	v_and_b32_e32 v29, 0xffff0000, v29
	v_writelane_b32 v255, s6, 60
	v_pk_mul_f32 v[70:71], v[142:143], v[54:55]
	v_pk_mul_f32 v[54:55], v[142:143], v[50:51]
	v_pk_mul_f32 v[76:77], v[140:141], v[48:49]
	v_pk_mul_f32 v[50:51], v[142:143], v[42:43]
	v_pk_mul_f32 v[48:49], v[140:141], v[40:41]
	v_pk_mul_f32 v[42:43], v[142:143], v[38:39]
	v_pk_mul_f32 v[40:41], v[140:141], v[28:29]
	v_pk_mul_f32 v[38:39], v[132:133], v[26:27]
	v_lshlrev_b32_e32 v26, 16, v86
	v_and_b32_e32 v27, 0xffff0000, v86
	v_lshlrev_b32_e32 v28, 16, v87
	v_and_b32_e32 v29, 0xffff0000, v87
	v_lshlrev_b32_e32 v86, 16, v88
	v_and_b32_e32 v87, 0xffff0000, v88
	v_lshlrev_b32_e32 v88, 16, v89
	v_and_b32_e32 v89, 0xffff0000, v89
	v_writelane_b32 v255, s7, 61
	v_pk_mul_f32 v[36:37], v[138:139], v[36:37]
	v_pk_mul_f32 v[34:35], v[136:137], v[34:35]
	v_pk_mul_f32 v[32:33], v[138:139], v[32:33]
	v_pk_mul_f32 v[30:31], v[136:137], v[30:31]
	v_pk_mul_f32 v[24:25], v[138:139], v[24:25]
	v_pk_mul_f32 v[22:23], v[136:137], v[22:23]
	v_pk_mul_f32 v[16:17], v[138:139], v[16:17]
	v_pk_mul_f32 v[14:15], v[136:137], v[14:15]
	v_pk_mul_f32 v[20:21], v[138:139], v[20:21]
	v_pk_mul_f32 v[18:19], v[136:137], v[18:19]
	v_pk_mul_f32 v[12:13], v[138:139], v[12:13]
	v_pk_mul_f32 v[10:11], v[136:137], v[10:11]
	v_pk_mul_f32 v[8:9], v[138:139], v[8:9]
	v_pk_mul_f32 v[6:7], v[136:137], v[6:7]
	v_pk_mul_f32 v[4:5], v[138:139], v[4:5]
	v_pk_mul_f32 v[2:3], v[136:137], v[2:3]
	v_pk_mul_f32 v[28:29], v[144:145], v[28:29]
	v_pk_mul_f32 v[26:27], v[142:143], v[26:27]
	v_pk_mul_f32 v[88:89], v[146:147], v[88:89]
	v_pk_mul_f32 v[86:87], v[134:135], v[86:87]
	s_mov_b32 s47, 0
	v_cmp_eq_u32_e64 s[38:39], 0, v154
	s_ashr_i32 s77, s65, 31
	v_or_b32_e32 v160, s12, v155
	s_add_u32 s81, s18, -2
	v_add_u32_e32 v161, 0, v156
	v_readlane_b32 s89, v255, 25
	v_readlane_b32 s86, v255, 27
	s_branch .LBB0_474
